# HID and PLE-projection (PP) epilogue stores write-through sc1, plus phase-B rewrites
# baseline (speedup 1.0000x reference)
.LBB0_1055:
	v_lshl_add_u32 v136, s85, 8, v132
	v_lshl_or_b32 v138, s84, 8, v134
	v_ashrrev_i32_e32 v137, 31, v136
	v_lshlrev_b64 v[140:141], 11, v[136:137]
	v_ashrrev_i32_e32 v139, 31, v138
	v_cvt_pk_bf16_f32 v126, v126, v127
	v_cvt_pk_bf16_f32 v127, v128, v129
	v_cvt_pk_bf16_f32 v128, v122, v123
	v_cvt_pk_bf16_f32 v129, v124, v125
	v_lshl_add_u64 v[122:123], s[4:5], 0, v[140:141]
	v_lshlrev_b64 v[124:125], 1, v[138:139]
	v_lshl_add_u64 v[122:123], v[122:123], 0, v[124:125]
	global_store_dwordx4 v[122:123], v[126:129], off sc1
	v_cvt_pk_bf16_f32 v114, v114, v115
	v_cvt_pk_bf16_f32 v115, v116, v117
	v_cvt_pk_bf16_f32 v116, v106, v107
	v_or_b32_e32 v106, 16, v136
	v_ashrrev_i32_e32 v107, 31, v106
	v_cvt_pk_bf16_f32 v117, v108, v109
	global_store_dwordx4 v[122:123], v[114:117], off offset:256 sc1
	s_mov_b32 s12, 0x40000
	s_mov_b64 s[86:87], 0x30080
	v_lshlrev_b64 v[114:115], 11, v[106:107]
	v_cvt_pk_bf16_f32 v106, v118, v119
	v_cvt_pk_bf16_f32 v107, v120, v121
	v_cvt_pk_bf16_f32 v108, v110, v111
	v_lshl_add_u64 v[110:111], s[4:5], 0, v[114:115]
	v_lshl_add_u64 v[110:111], v[110:111], 0, v[124:125]
	v_cvt_pk_bf16_f32 v109, v112, v113
	global_store_dwordx4 v[110:111], v[106:109], off sc1
	v_cvt_pk_bf16_f32 v98, v98, v99
	v_cvt_pk_bf16_f32 v99, v100, v101
	v_cvt_pk_bf16_f32 v100, v90, v91
	v_or_b32_e32 v90, 32, v136
	v_ashrrev_i32_e32 v91, 31, v90
	v_cvt_pk_bf16_f32 v101, v92, v93
	global_store_dwordx4 v[110:111], v[98:101], off offset:256 sc1
	s_nop 1
	v_lshlrev_b64 v[98:99], 11, v[90:91]
	v_cvt_pk_bf16_f32 v90, v102, v103
	v_cvt_pk_bf16_f32 v91, v104, v105
	v_cvt_pk_bf16_f32 v92, v94, v95
	v_lshl_add_u64 v[94:95], s[4:5], 0, v[98:99]
	v_lshl_add_u64 v[94:95], v[94:95], 0, v[124:125]
	v_cvt_pk_bf16_f32 v93, v96, v97
	global_store_dwordx4 v[94:95], v[90:93], off sc1
	v_cvt_pk_bf16_f32 v82, v82, v83
	v_cvt_pk_bf16_f32 v83, v84, v85
	v_cvt_pk_bf16_f32 v84, v74, v75
	v_or_b32_e32 v74, 48, v136
	v_ashrrev_i32_e32 v75, 31, v74
	v_cvt_pk_bf16_f32 v85, v76, v77
	global_store_dwordx4 v[94:95], v[82:85], off offset:256 sc1
	s_nop 1
	v_lshlrev_b64 v[82:83], 11, v[74:75]
	v_cvt_pk_bf16_f32 v74, v86, v87
	v_cvt_pk_bf16_f32 v75, v88, v89
	v_cvt_pk_bf16_f32 v76, v78, v79
	v_lshl_add_u64 v[78:79], s[4:5], 0, v[82:83]
	v_lshl_add_u64 v[78:79], v[78:79], 0, v[124:125]
	v_cvt_pk_bf16_f32 v77, v80, v81
	global_store_dwordx4 v[78:79], v[74:77], off sc1
	v_cvt_pk_bf16_f32 v70, v70, v71
	v_cvt_pk_bf16_f32 v71, v72, v73
	v_cvt_pk_bf16_f32 v72, v66, v67
	v_cvt_pk_bf16_f32 v73, v68, v69
	global_store_dwordx4 v[78:79], v[70:73], off offset:256 sc1
	v_cvt_pk_bf16_f32 v62, v62, v63
	v_cvt_pk_bf16_f32 v63, v64, v65
	v_cvt_pk_bf16_f32 v64, v58, v59
	v_cvt_pk_bf16_f32 v65, v60, v61
	v_add_co_u32_e32 v60, vcc, s12, v122
	v_lshl_add_u64 v[58:59], v[122:123], 0, s[28:29]
	s_nop 0
	v_addc_co_u32_e32 v61, vcc, 0, v123, vcc
	s_mov_b64 s[12:13], 0x48000
	global_store_dwordx4 v[60:61], v[62:65], off sc1
	v_cvt_pk_bf16_f32 v50, v50, v51
	v_cvt_pk_bf16_f32 v51, v52, v53
	v_cvt_pk_bf16_f32 v52, v42, v43
	v_cvt_pk_bf16_f32 v53, v44, v45
	global_store_dwordx4 v[58:59], v[50:53], off offset:256 sc1
	v_cvt_pk_bf16_f32 v42, v54, v55
	v_cvt_pk_bf16_f32 v43, v56, v57
	v_cvt_pk_bf16_f32 v44, v46, v47
	v_lshl_add_u64 v[46:47], v[122:123], 0, s[12:13]
	s_mov_b32 s12, 0x48000
	v_cvt_pk_bf16_f32 v45, v48, v49
	v_add_co_u32_e32 v48, vcc, s12, v122
	s_mov_b64 s[12:13], 0x50000
	s_nop 0
	v_addc_co_u32_e32 v49, vcc, 0, v123, vcc
	global_store_dwordx4 v[48:49], v[42:45], off sc1
	v_cvt_pk_bf16_f32 v34, v34, v35
	v_cvt_pk_bf16_f32 v35, v36, v37
	v_cvt_pk_bf16_f32 v36, v26, v27
	v_cvt_pk_bf16_f32 v37, v28, v29
	global_store_dwordx4 v[46:47], v[34:37], off offset:256 sc1
	v_cvt_pk_bf16_f32 v26, v38, v39
	v_cvt_pk_bf16_f32 v27, v40, v41
	v_cvt_pk_bf16_f32 v28, v30, v31
	v_lshl_add_u64 v[30:31], v[122:123], 0, s[12:13]
	s_mov_b32 s12, 0x50000
	v_cvt_pk_bf16_f32 v29, v32, v33
	v_add_co_u32_e32 v32, vcc, s12, v122
	s_mov_b32 s12, 0x58000
	s_nop 0
	v_addc_co_u32_e32 v33, vcc, 0, v123, vcc
	global_store_dwordx4 v[32:33], v[26:29], off sc1
	v_cvt_pk_bf16_f32 v18, v18, v19
	v_cvt_pk_bf16_f32 v19, v20, v21
	v_cvt_pk_bf16_f32 v20, v10, v11
	v_cvt_pk_bf16_f32 v21, v12, v13
	global_store_dwordx4 v[30:31], v[18:21], off offset:256 sc1
	v_cvt_pk_bf16_f32 v10, v22, v23
	v_cvt_pk_bf16_f32 v11, v24, v25
	v_cvt_pk_bf16_f32 v12, v14, v15
	v_cvt_pk_bf16_f32 v13, v16, v17
	v_add_co_u32_e32 v16, vcc, s12, v122
	v_lshl_add_u64 v[14:15], v[122:123], 0, s[2:3]
	s_nop 0
	v_addc_co_u32_e32 v17, vcc, 0, v123, vcc
	s_andn2_b64 vcc, exec, s[52:53]
	s_mov_b64 s[52:53], -1
	global_store_dwordx4 v[16:17], v[10:13], off sc1
	v_cvt_pk_bf16_f32 v6, v6, v7
	v_cvt_pk_bf16_f32 v7, v8, v9
	v_cvt_pk_bf16_f32 v8, v2, v3
	v_cvt_pk_bf16_f32 v9, v4, v5
	global_store_dwordx4 v[14:15], v[6:9], off offset:256 sc1
	s_cbranch_vccnz .LBB0_1048
	s_andn2_b64 vcc, exec, s[0:1]
	s_cbranch_vccnz .LBB0_1047
	s_barrier
	s_branch .LBB0_1047
